# branch-GEMM phase of both layers: split-K mini unit runs first on workgroups < 96
# baseline (speedup 1.0000x reference)
.LBB0_611:
	s_and_b64 vcc, exec, s[6:7]
	s_cbranch_vccz .LBB0_702
	v_mov_b32_e32 v14, v183
	v_mov_b32_e32 v174, 1
	v_ashrrev_i32_e32 v1, 31, v14
	v_lshrrev_b32_e32 v1, 26, v1
	v_add_u32_e32 v1, v14, v1
	v_ashrrev_i32_e32 v8, 6, v1
	v_bfe_i32 v1, v14, 27, 1
	v_lshlrev_b32_e32 v0, 4, v14
	v_lshrrev_b32_e32 v1, 22, v1
	v_add_u32_e32 v1, v0, v1
	v_and_b32_e32 v1, 0xfffffc00, v1
	v_sub_u32_e32 v1, v0, v1
	v_lshrrev_b32_e32 v2, 4, v1
	v_bitop3_b32 v1, v2, v1, 32 bitop3:0x6c
	v_ashrrev_i32_e32 v3, 31, v1
	v_lshrrev_b32_e32 v3, 26, v3
	v_add_u32_e32 v3, v1, v3
	v_lshlrev_b32_e32 v2, 3, v8
	v_ashrrev_i32_e32 v9, 6, v3
	v_and_b32_e32 v3, 0xc0, v3
	v_and_b32_e32 v2, -16, v2
	v_sub_u32_e32 v1, v1, v3
	v_add_u32_e32 v2, v9, v2
	v_ashrrev_i16_sdwa v1, v174, sext(v1) dst_sel:DWORD dst_unused:UNUSED_PAD src0_sel:DWORD src1_sel:BYTE_0
	v_lshlrev_b32_e32 v4, 5, v8
	v_bfe_i32 v10, v1, 0, 16
	v_lshlrev_b32_e32 v1, 1, v2
	v_lshrrev_b32_e32 v3, 2, v2
	v_and_b32_e32 v5, 3, v9
	s_mov_b32 s6, 0x1fffe0
	v_and_b32_e32 v4, 32, v4
	v_and_b32_e32 v1, 24, v1
	v_and_b32_e32 v3, 4, v3
	v_and_or_b32 v5, v2, s6, v5
	v_or3_b32 v1, v5, v3, v1
	v_add_lshl_u32 v3, v4, v10, 1
	v_add_u32_e32 v0, 0x2000, v0
	v_lshl_add_u32 v130, v1, 11, v3
	v_ashrrev_i32_e32 v1, 31, v0
	v_lshrrev_b32_e32 v1, 22, v1
	v_add_u32_e32 v1, v0, v1
	v_ashrrev_i32_e32 v11, 10, v1
	v_mul_i32_i24_e32 v1, 0x400, v11
	v_sub_u32_e32 v0, v0, v1
	v_lshrrev_b32_e32 v1, 4, v0
	v_bitop3_b32 v0, v1, v0, 32 bitop3:0x6c
	v_lshl_add_u32 v128, v2, 11, v3
	v_ashrrev_i32_e32 v2, 31, v0
	v_lshrrev_b32_e32 v2, 26, v2
	v_lshlrev_b32_e32 v1, 3, v11
	v_add_u32_e32 v2, v0, v2
	v_and_b32_e32 v1, -16, v1
	v_ashrrev_i32_e32 v12, 6, v2
	v_add_u32_e32 v1, v12, v1
	v_and_b32_e32 v4, 3, v12
	v_and_or_b32 v4, v1, s6, v4
	s_ashr_i32 s6, s20, 31
	s_lshr_b32 s6, s6, 29
	s_add_i32 s6, s20, s6
	s_ashr_i32 s6, s6, 3
	s_lshl_b32 s8, s20, 5
	s_mulk_i32 s6, 0xff01
	s_add_i32 s6, s6, s8
	s_ashr_i32 s8, s6, 31
	s_lshr_b32 s8, s8, 26
	s_add_i32 s8, s6, s8
	s_ashr_i32 s9, s8, 6
	s_andn2_b32 s8, s8, 63
	s_sub_i32 s8, s6, s8
	s_bfe_i32 s6, s8, 0x80000
	s_bfe_u32 s6, s6, 0x3000c
	s_add_i32 s10, s8, s6
	s_bfe_i32 s6, s10, 0x80000
	s_and_b32 s10, s10, 0xf8
	s_sub_i32 s8, s8, s10
	s_lshl_b32 s9, s9, 3
	s_sext_i32_i16 s6, s6
	s_sext_i32_i8 s8, s8
	v_readfirstlane_b32 s7, v14
	s_lshr_b32 s6, s6, 3
	s_add_i32 s10, s9, s8
	v_and_b32_e32 v2, 0xc0, v2
	s_ashr_i32 s17, s7, 6
	s_ashr_i32 s11, s10, 31
	s_bfe_i64 s[8:9], s[6:7], 0x100000
	s_ashr_i32 s16, s7, 8
	v_sub_u32_e32 v0, v0, v2
	s_lshl_b32 s28, s17, 10
	s_lshl_b64 s[12:13], s[10:11], 19
	s_lshl_b64 s[8:9], s[8:9], 19
	v_ashrrev_i16_sdwa v0, v174, sext(v0) dst_sel:DWORD dst_unused:UNUSED_PAD src0_sel:DWORD src1_sel:BYTE_0
	s_add_u32 s8, s38, s8
	v_lshlrev_b32_e32 v3, 5, v11
	v_bfe_i32 v13, v0, 0, 16
	v_lshlrev_b32_e32 v0, 1, v1
	v_lshrrev_b32_e32 v2, 2, v1
	s_addc_u32 s9, s39, s9
	s_cmpk_lt_i32 s20, 0x60
	s_cbranch_scc0 .Lmf_b_L0
	s_lshr_b32 s14, s20, 5
	s_lshl_b32 s14, s14, 22
	s_and_b32 s15, s20, 7
	s_lshl_b32 s15, s15, 19
	s_add_i32 s14, s14, s15
	s_bfe_u32 s15, s20, 0x20003
	s_lshl_b32 s15, s15, 9
	s_add_i32 s14, s14, s15
	s_add_u32 s8, s38, s14
	s_addc_u32 s9, s39, 0
.Lmf_b_L0:
	s_add_i32 s11, s28, 16
	v_and_b32_e32 v3, 32, v3
	v_and_b32_e32 v0, 24, v0
	v_and_b32_e32 v2, 4, v2
	s_add_i32 m0, s11, 0x10000
	v_or3_b32 v0, v4, v2, v0
	v_add_lshl_u32 v2, v3, v13, 1
	global_load_lds_dwordx4 v130, s[8:9]
	s_add_i32 m0, s11, 0x12000
	v_lshl_add_u32 v134, v0, 11, v2
	s_add_u32 s14, s8, 0x40000
	global_load_lds_dwordx4 v134, s[8:9]
	s_addc_u32 s15, s9, 0
	s_add_i32 m0, s11, 0x14000
	v_lshl_add_u32 v132, v1, 11, v2
	global_load_lds_dwordx4 v130, s[14:15]
	s_add_i32 m0, s11, 0x16000
	v_mov_b32_e32 v131, 0
	global_load_lds_dwordx4 v134, s[14:15]
	s_add_u32 s14, s36, s12
	s_addc_u32 s15, s37, s13
	s_cmpk_lt_i32 s20, 0x60
	s_cbranch_scc0 .Lmf_a_L0
	s_lshr_b32 s12, s20, 5
	s_mul_i32 s12, s12, 0x1080000
	s_add_i32 s12, s12, 0x1000000
	s_bfe_u32 s13, s20, 0x20003
	s_lshl_b32 s13, s13, 9
	s_add_i32 s12, s12, s13
	s_add_u32 s14, s36, s12
	s_addc_u32 s15, s37, 0
.Lmf_a_L0:
	s_add_i32 s29, s11, 0x2000
	s_mov_b32 m0, s11
	s_add_u32 s12, s14, 0x40000
	global_load_lds_dwordx4 v128, s[14:15]
	s_mov_b32 m0, s29
	s_addc_u32 s13, s15, 0
	s_add_i32 s30, s11, 0x4000
	global_load_lds_dwordx4 v132, s[14:15]
	s_mov_b32 m0, s30
	s_add_i32 s56, s11, 0x6000
	global_load_lds_dwordx4 v128, s[12:13]
	s_mov_b32 m0, s56
	v_mov_b32_e32 v135, v131
	global_load_lds_dwordx4 v132, s[12:13]
	v_mov_b32_e32 v129, v131
	v_mov_b32_e32 v133, v131
	s_cmp_eq_u32 s16, 1
	s_mov_b32 s86, 16
	v_lshl_add_u64 v[6:7], s[8:9], 0, v[130:131]
	v_lshl_add_u64 v[4:5], s[8:9], 0, v[134:135]
	v_lshl_add_u64 v[0:1], s[14:15], 0, v[128:129]
	s_cselect_b64 s[12:13], -1, 0
	s_cmp_lg_u32 s16, 1
	v_lshl_add_u64 v[2:3], s[14:15], 0, v[132:133]
	s_cbranch_scc1 .LBB0_614
	s_barrier
.LBB0_614:
	v_and_b32_e32 v15, 15, v14
	s_lshl_b32 s17, s17, 5
	v_lshl_or_b32 v136, s16, 6, v15
	s_lshl_b32 s26, s16, 13
	s_and_b32 s27, s17, 0x60
	s_mov_b64 s[16:17], 0x80
	s_add_i32 m0, s11, 0x18000
	v_lshl_add_u64 v[6:7], v[6:7], 0, s[16:17]
	s_lshl_b32 s31, s27, 7
	s_waitcnt vmcnt(2)
	s_barrier
	global_load_lds_dwordx4 v[6:7], off
	v_lshl_add_u64 v[4:5], v[4:5], 0, s[16:17]
	s_add_i32 m0, s11, 0x1a000
	s_add_i32 s57, s11, 0x8000
	s_add_i32 s58, s11, 0xa000
	global_load_lds_dwordx4 v[4:5], off
	v_lshl_add_u64 v[0:1], v[0:1], 0, s[16:17]
	s_mov_b32 m0, s57
	s_add_u32 s24, s8, 0x40080
	global_load_lds_dwordx4 v[0:1], off
	v_lshl_add_u64 v[0:1], v[2:3], 0, s[16:17]
	s_mov_b32 m0, s58
	s_addc_u32 s25, s9, 0
	global_load_lds_dwordx4 v[0:1], off
	s_add_i32 m0, s11, 0x1c000
	v_lshl_add_u64 v[0:1], s[24:25], 0, v[130:131]
	global_load_lds_dwordx4 v[0:1], off
	v_lshl_add_u64 v[0:1], s[24:25], 0, v[134:135]
	s_add_i32 m0, s11, 0x1e000
	v_add_u32_e32 v3, 0x2000, v136
	global_load_lds_dwordx4 v[0:1], off
	v_or_b32_e32 v0, 16, v136
	v_ashrrev_i32_e32 v1, 31, v0
	v_lshlrev_b64 v[140:141], 13, v[0:1]
	v_or_b32_e32 v0, 32, v136
	v_ashrrev_i32_e32 v1, 31, v0
	v_lshlrev_b64 v[142:143], 13, v[0:1]
	v_or_b32_e32 v0, 48, v136
	v_ashrrev_i32_e32 v1, 31, v0
	v_add_u32_e32 v4, 0x2010, v136
	v_add_u32_e32 v5, 0x2020, v136
	v_add_u32_e32 v6, 0x2030, v136
	v_lshlrev_b64 v[144:145], 13, v[0:1]
	s_movk_i32 s63, 0x1800
	v_mov_b64_e32 v[0:1], s[0:1]
	s_sext_i32_i8 s59, s6
	s_cmpk_lt_u32 s7, 0x100
	v_mad_i64_i32 v[146:147], s[6:7], v3, s63, v[0:1]
	v_mad_i64_i32 v[148:149], s[6:7], v4, s63, v[0:1]
	v_mad_i64_i32 v[150:151], s[6:7], v5, s63, v[0:1]
	v_mad_i64_i32 v[152:153], s[6:7], v6, s63, v[0:1]
	v_lshlrev_b32_e32 v0, 14, v11
	v_and_b32_e32 v0, 0xffff8000, v0
	v_lshl_add_u32 v0, v12, 11, v0
	v_and_b32_e32 v1, 1, v11
	v_lshrrev_b32_e32 v16, 1, v14
	v_lshl_or_b32 v0, v1, 6, v0
	v_and_b32_e32 v16, 24, v16
	v_lshl_add_u32 v154, v13, 1, v0
	v_lshlrev_b32_e32 v0, 14, v8
	v_lshlrev_b32_e32 v17, 1, v16
	v_lshlrev_b32_e32 v14, 2, v14
	v_and_b32_e32 v0, 0xffff8000, v0
	v_lshl_or_b32 v15, v15, 6, v17
	v_and_b32_e32 v14, 32, v14
	s_waitcnt vmcnt(6)
	s_cselect_b64 s[34:35], -1, 0
	s_cmpk_lt_i32 s20, 0x60
	v_lshl_add_u32 v0, v9, 11, v0
	v_and_b32_e32 v1, 1, v8
	v_bitop3_b32 v175, v15, s31, v14 bitop3:0xde
	v_bitop3_b32 v2, v15, s26, v14 bitop3:0xde
	v_ashrrev_i32_e32 v137, 31, v136
	s_cselect_b64 s[52:53], -1, 0
	s_bfe_u32 s61, s20, 0x20003
	s_mov_b32 s55, 0
	v_lshl_or_b32 v0, v1, 6, v0
	s_add_i32 s64, 16, 0x10000
	s_add_i32 s65, 16, 0x14000
	v_or_b32_e32 v176, s27, v16
	v_lshlrev_b64 v[138:139], 13, v[136:137]
	s_ashr_i32 s60, s20, 5
	s_lshl_b32 s54, s61, 9
	s_and_b32 s62, s20, 7
	v_mov_b32_e32 v155, v131
	v_lshl_add_u32 v156, v10, 1, v0
	v_mov_b32_e32 v157, v131
	s_mov_b32 s90, -1
	s_mov_b64 s[72:73], 0x100
	v_add_u32_e32 v137, s64, v175
	v_add_u32_e32 v177, s65, v175
	v_add_u32_e32 v178, 16, v2
	s_mov_b32 s74, 0x3b808081
	s_mov_b32 s31, s10
	s_mov_b32 s89, s59
	s_mov_b32 s91, s55
	s_mov_b32 s66, s55
	s_cmpk_lt_i32 s20, 0x60
	s_cselect_b32 s31, 32, s31
	s_cselect_b32 s89, s62, s89
	s_cselect_b32 s86, 4, s86
	s_cselect_b32 s90, s61, s90
	s_cselect_b32 s91, s60, s91
	s_barrier
	s_branch .LBB0_617

.LBB0_617:
	s_mov_b32 s6, s66
	s_add_i32 s66, s66, 1
	s_cmpk_lt_i32 s20, 0x60
	s_cselect_b32 vcc_lo, 3, 2
	s_cmp_lt_u32 s6, vcc_lo
	s_cselect_b64 s[6:7], -1, 0
	s_and_b64 vcc, exec, s[6:7]
	s_cbranch_vccnz .LBB0_619
	s_mov_b32 s76, 32
	s_mov_b32 s67, 4
	s_mov_b64 s[24:25], s[54:55]
	s_mov_b32 s88, s61
	s_mov_b32 s78, s62
	s_mov_b32 s80, s60
	s_branch .LBB0_620
.LBB0_619:
	s_mov_b64 s[24:25], 0
	s_mov_b32 s67, 16
	s_mov_b32 s88, -1
	s_mov_b32 s78, s59
	s_mov_b32 s76, s10
	s_cmpk_lt_i32 s20, 0x60
	s_cselect_b32 s80, 1, 0
	s_sub_i32 s80, s66, s80
